# pass A S1: strict/non-strict triangular mask select folded into one compare against t or t+1
# speedup vs baseline: 1.0149x; 1.0018x over previous
.LBB0_698:
	v_cndmask_b32_e64 v29, v34, 0, s[24:25]
	v_readlane_b32 s80, v233, 39
	v_add_f32_e32 v34, v35, v29
	v_readlane_b32 s81, v233, 40
	v_readlane_b32 s0, v233, 41
	v_readlane_b32 s1, v233, 42
	v_cndmask_b32_e64 v29, v29, v34, s[80:81]
	v_add_f32_e32 v32, v32, v29
	v_cndmask_b32_e64 v29, v29, v32, s[0:1]
	v_readlane_b32 s0, v233, 43
	v_add_f32_e32 v32, v33, v29
	v_readlane_b32 s1, v233, 44
	s_nop 1
	v_cndmask_b32_e64 v29, v29, v32, s[0:1]
	v_readlane_b32 s0, v233, 45
	v_add_f32_e32 v30, v30, v29
	v_readlane_b32 s1, v233, 46
	s_nop 0
	s_nop 0
	v_cndmask_b32_e64 v29, v29, v30, s[0:1]
	v_readlane_b32 s0, v233, 47
	v_add_f32_e32 v31, v31, v29
	v_readlane_b32 s1, v233, 48
	s_nop 1
	v_cndmask_b32_e64 v29, v29, v31, s[0:1]
	v_add_f32_e32 v18, v18, v29
	s_nop 1
	s_nop 0
	v_readlane_b32 s0, v233, 49
	v_readlane_b32 s1, v233, 50
	s_nop 1
	v_cndmask_b32_e64 v18, v29, v18, s[0:1]
	v_readlane_b32 s0, v233, 51
	v_add_f32_e32 v19, v19, v18
	v_readlane_b32 s1, v233, 52
	s_nop 1
	v_cndmask_b32_e64 v18, v18, v19, s[0:1]
	v_sqrt_f32_e32 v19, s46
	s_nop 0
	v_max_f32_e32 v19, 0x2b8cbccc, v19
	v_rcp_f32_e32 v19, v19
	s_nop 0
	v_mul_f32_e32 v19, v112, v19
	v_add_f32_e32 v109, v109, v18
	v_mul_f32_e32 v17, v19, v17
	v_sqrt_f32_e32 v29, s19
	s_nop 0
	v_max_f32_e32 v29, 0x2b8cbccc, v29
	v_rcp_f32_e32 v29, v29
	s_nop 0
	v_mul_f32_e32 v29, v111, v29
	v_mul_f32_e32 v15, v29, v15
	s_nop 0
	v_sqrt_f32_e32 v30, s18
	s_nop 0
	v_max_f32_e32 v30, 0x2b8cbccc, v30
	v_rcp_f32_e32 v30, v30
	s_nop 0
	v_mul_f32_e32 v114, v110, v30
	v_mul_f32_e32 v16, v114, v16
	s_nop 0
	v_sqrt_f32_e32 v30, s17
	s_nop 0
	v_max_f32_e32 v30, 0x2b8cbccc, v30
	v_rcp_f32_e32 v30, v30
	s_nop 0
	v_mul_f32_e32 v104, v104, v30
	v_mul_f32_e32 v14, v104, v14
	s_nop 0
	v_sqrt_f32_e32 v30, s9
	s_nop 0
	v_max_f32_e32 v30, 0x2b8cbccc, v30
	v_rcp_f32_e32 v30, v30
	s_nop 0
	v_mul_f32_e32 v100, v100, v30
	v_mul_f32_e32 v13, v100, v13
	s_nop 0
	v_sqrt_f32_e32 v30, s8
	s_nop 0
	v_max_f32_e32 v30, 0x2b8cbccc, v30
	v_rcp_f32_e32 v30, v30
	s_nop 0
	v_mul_f32_e32 v115, v99, v30
	v_lshlrev_b32_e32 v110, 16, v61
	v_mov_b32_e32 v111, s6
	v_mul_f32_e32 v11, v115, v11
	s_nop 0
	v_and_b32_e32 v31, 0xffff0000, v88
	v_sqrt_f32_e32 v30, s7
	s_nop 0
	v_max_f32_e32 v30, 0x2b8cbccc, v30
	v_rcp_f32_e32 v30, v30
	s_nop 0
	v_mul_f32_e32 v116, v98, v30
	v_lshlrev_b32_e32 v30, 16, v88
	v_lshlrev_b32_e32 v33, 16, v54
	v_lshlrev_b32_e32 v35, 16, v52
	v_lshlrev_b32_e32 v34, 16, v45
	v_mov_b32_e32 v32, v31
	v_pk_add_f32 v[30:31], v[30:31], v[34:35] neg_lo:[0,1] neg_hi:[0,1]
	v_pk_add_f32 v[98:99], v[34:35], v[32:33] neg_lo:[0,1] neg_hi:[0,1]
	v_pk_fma_f32 v[30:31], v[24:25], v[30:31], v[34:35] op_sel_hi:[0,1,1]
	v_pk_fma_f32 v[34:35], v[98:99], v[24:25], v[32:33] op_sel_hi:[1,0,1]
	v_mul_f32_e32 v32, s6, v79
	v_cmp_lt_f32_e32 vcc, s6, v78
	v_lshlrev_b32_e32 v99, 16, v66
	v_lshlrev_b32_e32 v98, 16, v56
	v_cndmask_b32_e32 v112, v111, v32, vcc
	v_sqrt_f32_e32 v113, v112
	v_lshlrev_b32_e32 v111, 16, v71
	v_pk_mov_b32 v[32:33], v[32:33], v[110:111] op_sel:[1,0]
	v_mul_f32_e32 v12, v116, v12
	v_add_u32_e32 v117, -1, v113
	v_fma_f32 v118, -v117, v113, v112
	v_cmp_ge_f32_e64 s[0:1], 0, v118
	v_add_u32_e32 v118, 1, v113
	v_pk_add_f32 v[32:33], v[32:33], v[98:99] neg_lo:[0,1] neg_hi:[0,1]
	v_cndmask_b32_e64 v117, v113, v117, s[0:1]
	v_fma_f32 v113, -v118, v113, v112
	v_cmp_lt_f32_e64 s[0:1], 0, v113
	v_pk_fma_f32 v[32:33], v[32:33], v[24:25], v[98:99] op_sel_hi:[1,0,1]
	s_nop 0
	v_cndmask_b32_e64 v113, v117, v118, s[0:1]
	v_mul_f32_e32 v117, 0x37800000, v113
	v_cndmask_b32_e32 v113, v113, v117, vcc
	v_cmp_class_f32_e32 vcc, v112, v77
	s_nop 1
	v_cndmask_b32_e32 v112, v113, v112, vcc
	v_max_f32_e32 v117, 0x2b8cbccc, v112
	v_div_scale_f32 v118, s[0:1], v117, v117, v97
	v_pk_add_f32 v[112:113], v[98:99], v[110:111] neg_lo:[0,1] neg_hi:[0,1]
	s_nop 0
	v_pk_fma_f32 v[98:99], v[112:113], v[24:25], v[110:111] op_sel_hi:[1,0,1]
	v_sqrt_f32_e32 v110, s6
	s_nop 0
	v_max_f32_e32 v110, 0x2b8cbccc, v110
	v_rcp_f32_e32 v110, v110
	s_nop 0
	v_mul_f32_e32 v97, v97, v110
	v_mul_f32_e32 v110, 0x3fb8aa3b, v18
	v_exp_f32_e32 v111, v110
	v_mul_f32_e32 v110, 0x3fb8aa3b, v109
	v_exp_f32_e32 v112, v110
	v_mul_f32_e32 v109, 0xbfb8aa3b, v109
	v_exp_f32_e32 v110, v109
	v_mul_f32_e32 v10, v97, v10
	v_mul_f32_e64 v97, v111, -v97
	v_mul_f32_e32 v96, v96, v112
	v_cvt_pk_bf16_f32 v109, v97, s0
	v_cvt_pk_bf16_f32 v96, v96, s0
	v_mul_f32_e32 v97, v10, v110
	v_mul_f32_e32 v111, v0, v110
	v_cvt_pk_bf16_f32 v113, v30, v31
	v_lshl_add_u32 v30, v28, 1, s74
	v_add_f32_e32 v31, v108, v18
	v_cvt_pk_bf16_f32 v97, v97, s0
	v_cvt_pk_bf16_f32 v111, v111, s0
	ds_write_b16 v30, v109
	ds_write_b16 v30, v96 offset:9216
	ds_write_b16 v30, v97 offset:18432
	ds_write_b16 v30, v111 offset:27648
	v_mul_f32_e32 v96, 0x3fb8aa3b, v31
	v_mul_f32_e32 v31, 0xbfb8aa3b, v31
	v_exp_f32_e32 v97, v96
	v_exp_f32_e32 v96, v31
	v_mul_f32_e64 v31, v112, -v116
	v_cvt_pk_bf16_f32 v112, v34, v35
	v_add_f32_e32 v34, v107, v18
	v_mul_f32_e32 v111, v4, v96
	v_mul_f32_e32 v35, 0x3fb8aa3b, v34
	v_cvt_pk_bf16_f32 v31, v31, s0
	v_mul_f32_e32 v94, v94, v97
	v_mul_f32_e32 v108, v12, v96
	v_cvt_pk_bf16_f32 v111, v111, s0
	v_exp_f32_e32 v35, v35
	v_mul_f32_e32 v34, 0xbfb8aa3b, v34
	v_cvt_pk_bf16_f32 v94, v94, s0
	v_cvt_pk_bf16_f32 v108, v108, s0
	ds_write_b16 v30, v31 offset:144
	ds_write_b16 v30, v94 offset:9360
	ds_write_b16 v30, v108 offset:18576
	ds_write_b16 v30, v111 offset:27792
	v_exp_f32_e32 v111, v34
	v_mul_f32_e64 v34, v97, -v115
	v_cvt_pk_bf16_f32 v94, v34, s0
	v_mul_f32_e32 v34, v92, v35
	v_cvt_pk_bf16_f32 v34, v34, s0
	v_mul_f32_e32 v92, v11, v111
	v_mul_f32_e32 v97, v1, v111
	v_cvt_pk_bf16_f32 v92, v92, s0
	v_cvt_pk_bf16_f32 v97, v97, s0
	ds_write_b16 v30, v94 offset:288
	ds_write_b16 v30, v34 offset:9504
	ds_write_b16 v30, v92 offset:18720
	ds_write_b16 v30, v97 offset:27936
	v_add_f32_e32 v34, v106, v18
	v_mul_f32_e32 v92, 0x3fb8aa3b, v34
	v_exp_f32_e32 v92, v92
	v_mul_f32_e32 v34, 0xbfb8aa3b, v34
	v_exp_f32_e32 v97, v34
	v_mul_f32_e64 v34, v35, -v100
	v_cvt_pk_bf16_f32 v100, v34, s0
	v_mul_f32_e32 v34, v90, v92
	v_cvt_pk_bf16_f32 v34, v34, s0
	v_mul_f32_e32 v35, v13, v97
	v_mul_f32_e32 v90, v5, v97
	v_cvt_pk_bf16_f32 v35, v35, s0
	v_cvt_pk_bf16_f32 v90, v90, s0
	ds_write_b16 v30, v100 offset:432
	ds_write_b16 v30, v34 offset:9648
	ds_write_b16 v30, v35 offset:18864
	ds_write_b16 v30, v90 offset:28080
	v_add_f32_e32 v34, v105, v18
	v_mul_f32_e32 v35, 0x3fb8aa3b, v34
	v_exp_f32_e32 v35, v35
	v_mul_f32_e32 v34, 0xbfb8aa3b, v34
	v_exp_f32_e32 v34, v34
	v_mul_f32_e64 v90, v92, -v104
	v_cvt_pk_bf16_f32 v105, v32, v33
	v_add_f32_e32 v32, v103, v18
	v_cvt_pk_bf16_f32 v92, v90, s0
	v_mul_f32_e32 v90, v95, v35
	v_mul_f32_e32 v33, 0x3fb8aa3b, v32
	v_cvt_pk_bf16_f32 v90, v90, s0
	v_mul_f32_e32 v95, v14, v34
	v_mul_f32_e32 v104, v6, v34
	v_exp_f32_e32 v33, v33
	v_mul_f32_e32 v32, 0xbfb8aa3b, v32
	v_cvt_pk_bf16_f32 v95, v95, s0
	v_cvt_pk_bf16_f32 v104, v104, s0
	ds_write_b16 v30, v92 offset:576
	ds_write_b16 v30, v90 offset:9792
	ds_write_b16 v30, v95 offset:19008
	ds_write_b16 v30, v104 offset:28224
	v_exp_f32_e32 v90, v32
	v_mul_f32_e64 v32, v35, -v114
	v_mul_f32_e32 v35, v93, v33
	v_cvt_pk_bf16_f32 v32, v32, s0
	v_cvt_pk_bf16_f32 v35, v35, s0
	v_mul_f32_e32 v93, v16, v90
	v_mul_f32_e32 v95, v8, v90
	v_cvt_pk_bf16_f32 v93, v93, s0
	v_cvt_pk_bf16_f32 v95, v95, s0
	ds_write_b16 v30, v32 offset:720
	ds_write_b16 v30, v35 offset:9936
	ds_write_b16 v30, v93 offset:19152
	ds_write_b16 v30, v95 offset:28368
	v_add_f32_e32 v35, v102, v18
	v_mul_f32_e32 v93, 0x3fb8aa3b, v35
	v_exp_f32_e32 v93, v93
	v_mul_f32_e32 v35, 0xbfb8aa3b, v35
	v_exp_f32_e32 v35, v35
	v_mul_f32_e64 v29, v33, -v29
	v_mul_f32_e32 v33, v91, v93
	v_cvt_pk_bf16_f32 v29, v29, s0
	v_cvt_pk_bf16_f32 v33, v33, s0
	v_mul_f32_e32 v91, v15, v35
	v_mul_f32_e32 v95, v7, v35
	v_add_f32_e32 v18, v101, v18
	v_cvt_pk_bf16_f32 v91, v91, s0
	v_cvt_pk_bf16_f32 v95, v95, s0
	ds_write_b16 v30, v29 offset:864
	ds_write_b16 v30, v33 offset:10080
	ds_write_b16 v30, v91 offset:19296
	ds_write_b16 v30, v95 offset:28512
	v_mul_f32_e32 v33, 0x3fb8aa3b, v18
	v_exp_f32_e32 v33, v33
	v_mul_f32_e32 v18, 0xbfb8aa3b, v18
	v_exp_f32_e32 v91, v18
	v_mul_f32_e64 v18, v93, -v19
	v_mul_f32_e32 v19, v89, v33
	v_cvt_pk_bf16_f32 v18, v18, s0
	v_cvt_pk_bf16_f32 v19, v19, s0
	v_mul_f32_e32 v33, v17, v91
	v_mul_f32_e32 v89, v9, v91
	v_cvt_pk_bf16_f32 v33, v33, s0
	v_cvt_pk_bf16_f32 v89, v89, s0
	ds_write_b16 v30, v18 offset:1008
	ds_write_b16 v30, v19 offset:10224
	ds_write_b16 v30, v33 offset:19440
	ds_write_b16 v30, v89 offset:28656
	v_lshlrev_b32_e32 v19, 16, v31
	v_or_b32_sdwa v30, v19, v109 dst_sel:DWORD dst_unused:UNUSED_PAD src0_sel:DWORD src1_sel:WORD_0
	v_lshlrev_b32_e32 v19, 16, v100
	v_lshlrev_b32_e32 v18, 16, v18
	v_or_b32_sdwa v31, v19, v94 dst_sel:DWORD dst_unused:UNUSED_PAD src0_sel:DWORD src1_sel:WORD_0
	v_lshlrev_b32_e32 v19, 16, v32
	v_or_b32_sdwa v33, v18, v29 dst_sel:DWORD dst_unused:UNUSED_PAD src0_sel:DWORD src1_sel:WORD_0
	v_mul_lo_u32 v18, v28, s76
	v_or_b32_sdwa v32, v19, v92 dst_sel:DWORD dst_unused:UNUSED_PAD src0_sel:DWORD src1_sel:WORD_0
	v_add_u32_e32 v29, s53, v18
	v_pk_mul_f32 v[18:19], v[2:3], v[110:111] op_sel_hi:[0,1]
	ds_write_b128 v29, v[30:33] offset:36864
	v_pk_mul_f32 v[30:31], v[2:3], v[96:97] op_sel_hi:[0,1]
	v_pk_mul_f32 v[10:11], v[10:11], v[18:19]
	v_pk_mul_f32 v[0:1], v[0:1], v[18:19]
	v_cvt_pk_bf16_f32 v32, v10, v11
	v_pk_mul_f32 v[10:11], v[12:13], v[30:31]
	v_cvt_pk_bf16_f32 v98, v98, v99
	v_cvt_pk_bf16_f32 v10, v10, v11
	v_and_b32_e32 v11, 0xffff0000, v10
	v_lshlrev_b32_e32 v10, 16, v10
	v_or_b32_sdwa v11, v11, v32 dst_sel:DWORD dst_unused:UNUSED_PAD src0_sel:DWORD src1_sel:WORD_1
	v_or_b32_sdwa v10, v10, v32 dst_sel:DWORD dst_unused:UNUSED_PAD src0_sel:DWORD src1_sel:WORD_0
	v_pk_mul_f32 v[32:33], v[2:3], v[34:35] op_sel_hi:[0,1]
	v_pk_mul_f32 v[34:35], v[2:3], v[90:91] op_sel_hi:[0,1]
	v_pk_mul_f32 v[12:13], v[14:15], v[32:33]
	s_mov_b64 s[0:1], -1
	v_cvt_pk_bf16_f32 v2, v12, v13
	v_pk_mul_f32 v[12:13], v[16:17], v[34:35]
	s_and_b64 vcc, exec, s[80:81]
	v_cvt_pk_bf16_f32 v12, v12, v13
	v_and_b32_e32 v13, 0xffff0000, v12
	v_lshlrev_b32_e32 v12, 16, v12
	v_or_b32_sdwa v13, v13, v2 dst_sel:DWORD dst_unused:UNUSED_PAD src0_sel:DWORD src1_sel:WORD_1
	v_or_b32_sdwa v12, v12, v2 dst_sel:DWORD dst_unused:UNUSED_PAD src0_sel:DWORD src1_sel:WORD_0
	v_cvt_pk_bf16_f32 v2, v0, v1
	v_pk_mul_f32 v[0:1], v[4:5], v[30:31]
	ds_write_b128 v29, v[10:13] offset:46080
	v_cvt_pk_bf16_f32 v0, v0, v1
	v_and_b32_e32 v1, 0xffff0000, v0
	v_lshlrev_b32_e32 v0, 16, v0
	v_or_b32_sdwa v5, v1, v2 dst_sel:DWORD dst_unused:UNUSED_PAD src0_sel:DWORD src1_sel:WORD_1
	v_or_b32_sdwa v4, v0, v2 dst_sel:DWORD dst_unused:UNUSED_PAD src0_sel:DWORD src1_sel:WORD_0
	v_pk_mul_f32 v[0:1], v[6:7], v[32:33]
	v_mov_b32_e32 v12, s55
	v_cvt_pk_bf16_f32 v2, v0, v1
	v_pk_mul_f32 v[0:1], v[8:9], v[34:35]
	s_nop 0
	v_cvt_pk_bf16_f32 v0, v0, v1
	v_and_b32_e32 v1, 0xffff0000, v0
	v_lshlrev_b32_e32 v0, 16, v0
	v_or_b32_sdwa v7, v1, v2 dst_sel:DWORD dst_unused:UNUSED_PAD src0_sel:DWORD src1_sel:WORD_1
	v_or_b32_sdwa v6, v0, v2 dst_sel:DWORD dst_unused:UNUSED_PAD src0_sel:DWORD src1_sel:WORD_0
	v_and_b32_e32 v0, 0xffff0000, v112
	v_lshlrev_b32_e32 v1, 16, v112
	ds_write_b128 v29, v[4:7] offset:55296
	v_or_b32_sdwa v5, v0, v113 dst_sel:DWORD dst_unused:UNUSED_PAD src0_sel:DWORD src1_sel:WORD_1
	v_or_b32_sdwa v4, v1, v113 dst_sel:DWORD dst_unused:UNUSED_PAD src0_sel:DWORD src1_sel:WORD_0
	v_and_b32_e32 v0, 0xffff0000, v98
	v_lshlrev_b32_e32 v1, 16, v98
	v_or_b32_sdwa v7, v0, v105 dst_sel:DWORD dst_unused:UNUSED_PAD src0_sel:DWORD src1_sel:WORD_1
	v_or_b32_sdwa v6, v1, v105 dst_sel:DWORD dst_unused:UNUSED_PAD src0_sel:DWORD src1_sel:WORD_0
	ds_write_b128 v29, v[4:7] offset:64512
	s_waitcnt lgkmcnt(0)
	s_barrier
	s_nop 0
	v_and_b32_e32 v0, 15, v28
	v_or_b32_e32 v92, s57, v0
	v_cndmask_b32_e64 v129, 1, 0, s[20:21]
	v_add_u32_e32 v129, v129, v92
	v_and_b32_e32 v1, -16, v28
	v_mul_u32_u24_e32 v34, 0x90, v92
	v_mad_u32_u24 v12, v0, s76, v12
	v_add3_u32 v4, s54, v34, v1
	v_add_u32_e32 v30, v12, v1
	ds_read_b128 v[8:11], v4
	ds_read_b128 v[4:7], v4 offset:64
	ds_read_b128 v[16:19], v30
	ds_read_b128 v[12:15], v30 offset:64
	v_ashrrev_i32_e32 v2, 4, v28
	v_lshlrev_b32_e32 v29, 2, v2
	v_lshlrev_b32_e32 v2, 3, v2
	v_add_u32_e32 v33, s56, v2
	v_or_b32_e32 v89, v29, v69
	v_or_b32_e32 v32, 2, v29
	v_or_b32_e32 v31, 3, v29
	v_add_u32_e32 v34, v33, v34
	s_cbranch_vccz .LBB0_700
	s_waitcnt lgkmcnt(1)
	v_mfma_f32_16x16x32_bf16 v[94:97], v[16:19], v[8:11], 0
	v_cmp_lt_i32_e32 vcc, v29, v129
	s_mov_b64 s[0:1], 0
	s_waitcnt lgkmcnt(0)
	v_mfma_f32_16x16x32_bf16 v[94:97], v[12:15], v[4:7], v[94:97]
	v_mov_b32_e32 v90, s16
	s_nop 6
	v_cndmask_b32_e32 v35, v90, v94, vcc
	v_cmp_gt_i32_e32 vcc, v92, v89
	s_nop 1
	v_cndmask_b32_e32 v90, 0, v95, vcc
	v_cmp_lt_i32_e32 vcc, v32, v129
	v_cvt_pk_bf16_f32 v90, v35, v90
	s_nop 0
	v_cndmask_b32_e32 v91, 0, v96, vcc
	v_cmp_lt_i32_e32 vcc, v31, v129
	s_nop 1
	v_cndmask_b32_e32 v93, 0, v97, vcc
	v_cvt_pk_bf16_f32 v91, v91, v93
	ds_write_b64 v34, v[90:91]

.LBB0_706:
	v_add_u32_e32 v16, 16, v29
	v_cmp_lt_i32_e32 vcc, v16, v129
	v_add_u32_e32 v16, 17, v29
	s_nop 0
	s_nop 3
	v_cndmask_b32_e32 v12, 0, v12, vcc
	v_cmp_lt_i32_e32 vcc, v16, v129
	v_add_u32_e32 v16, 18, v29
	s_nop 0
	v_cndmask_b32_e32 v13, 0, v13, vcc
	v_cmp_lt_i32_e32 vcc, v16, v129
	v_cvt_pk_bf16_f32 v12, v12, v13
	v_add_u32_e32 v16, 19, v29
	v_cndmask_b32_e32 v14, 0, v14, vcc
	v_cmp_lt_i32_e32 vcc, v16, v129
	s_nop 1
	v_cndmask_b32_e32 v15, 0, v15, vcc
	v_cvt_pk_bf16_f32 v13, v14, v15
	ds_write_b64 v34, v[12:13] offset:32

.LBB0_710:
	v_add_u32_e32 v16, 32, v29
	v_cmp_lt_i32_e32 vcc, v16, v129
	v_add_u32_e32 v16, 33, v29
	s_nop 0
	s_nop 3
	v_cndmask_b32_e32 v12, 0, v12, vcc
	v_cmp_lt_i32_e32 vcc, v16, v129
	v_add_u32_e32 v16, 34, v29
	s_nop 0
	v_cndmask_b32_e32 v13, 0, v13, vcc
	v_cmp_lt_i32_e32 vcc, v16, v129
	v_cvt_pk_bf16_f32 v12, v12, v13
	v_add_u32_e32 v16, 35, v29
	v_cndmask_b32_e32 v14, 0, v14, vcc
	v_cmp_lt_i32_e32 vcc, v16, v129
	s_nop 1
	v_cndmask_b32_e32 v15, 0, v15, vcc
	v_cvt_pk_bf16_f32 v13, v14, v15
	ds_write_b64 v34, v[12:13] offset:64
	s_branch .LBB0_720

.LBB0_724:
	v_or_b32_e32 v34, s60, v0
	v_cndmask_b32_e64 v128, 1, 0, s[20:21]
	v_add_u32_e32 v128, v128, v34
	v_mul_u32_u24_e32 v91, 0x90, v34
	v_add3_u32 v4, s54, v91, v1
	ds_read_b128 v[8:11], v4
	ds_read_b128 v[4:7], v4 offset:64
	ds_read_b128 v[16:19], v30
	ds_read_b128 v[12:15], v30 offset:64
	s_mov_b64 s[6:7], -1
	s_and_b64 vcc, exec, s[4:5]
	v_add_u32_e32 v33, v33, v91
	s_cbranch_vccnz .LBB0_728
	s_waitcnt lgkmcnt(1)
	v_mfma_f32_16x16x32_bf16 v[92:95], v[16:19], v[8:11], 0
	v_cmp_lt_i32_e32 vcc, v29, v128
	s_waitcnt lgkmcnt(0)
	v_mfma_f32_16x16x32_bf16 v[92:95], v[12:15], v[4:7], v[92:95]
	v_mov_b32_e32 v96, s16
	s_nop 6
	v_cndmask_b32_e32 v91, v96, v92, vcc
	v_cmp_gt_i32_e32 vcc, v34, v89
	s_nop 1
	v_cndmask_b32_e32 v89, 0, v93, vcc
	v_cmp_lt_i32_e32 vcc, v32, v128
	s_nop 1
	v_cndmask_b32_e32 v32, 0, v94, vcc
	v_cmp_lt_i32_e32 vcc, v31, v128
	v_cvt_pk_bf16_f32 v92, v91, v89
	s_nop 0
	v_cndmask_b32_e32 v31, 0, v95, vcc
	v_cvt_pk_bf16_f32 v93, v32, v31
	ds_write_b64 v33, v[92:93]
	v_add_u32_e32 v32, s60, v29
	v_add_u32_e32 v31, s61, v90
	s_cbranch_execz .LBB0_729

.LBB0_727:
	s_waitcnt lgkmcnt(0)
	ds_read_b128 v[12:15], v30 offset:2304
	ds_read_b128 v[16:19], v30 offset:2368
	v_add_u32_e32 v35, 16, v29
	v_cmp_lt_i32_e32 vcc, v35, v34
	v_mov_b32_e32 v90, s16
	s_waitcnt lgkmcnt(1)
	v_mfma_f32_16x16x32_bf16 v[12:15], v[12:15], v[8:11], 0
	v_cndmask_b32_e64 v89, 0, 1, vcc
	v_cmp_le_i32_e32 vcc, v35, v34
	s_waitcnt lgkmcnt(0)
	v_mfma_f32_16x16x32_bf16 v[12:15], v[16:19], v[4:7], v[12:15]
	v_cndmask_b32_e64 v35, 0, 1, vcc
	v_cndmask_b32_e64 v35, v35, v89, s[20:21]
	v_add_u32_e32 v89, 17, v29
	v_and_b32_e32 v35, 1, v35
	v_cmp_lt_i32_e32 vcc, v89, v34
	s_nop 1
	v_cndmask_b32_e64 v91, 0, 1, vcc
	v_cmp_eq_u32_e32 vcc, 1, v35
	s_nop 1
	v_cndmask_b32_e32 v12, v90, v12, vcc
	v_cmp_le_i32_e32 vcc, v89, v34
	s_nop 1
	v_cndmask_b32_e64 v16, 0, 1, vcc
	v_cndmask_b32_e64 v16, v16, v91, s[20:21]
	v_and_b32_e32 v16, 1, v16
	v_cmp_eq_u32_e32 vcc, 1, v16
	v_add_u32_e32 v16, 18, v29
	s_nop 0
	v_cndmask_b32_e32 v13, 0, v13, vcc
	v_cmp_lt_i32_e32 vcc, v16, v128
	v_cvt_pk_bf16_f32 v12, v12, v13
	v_add_u32_e32 v16, 19, v29
	v_cndmask_b32_e32 v14, 0, v14, vcc
	v_cmp_lt_i32_e32 vcc, v16, v128
	s_nop 1
	v_cndmask_b32_e32 v15, 0, v15, vcc
	v_cvt_pk_bf16_f32 v13, v14, v15
	ds_write_b64 v33, v[12:13] offset:32
	s_cbranch_execnz .LBB0_733
	s_branch .LBB0_731

.LBB0_736:
	v_add_u32_e32 v16, 32, v29
	v_cmp_lt_i32_e32 vcc, v16, v128
	v_add_u32_e32 v16, 33, v29
	s_nop 0
	s_nop 3
	v_cndmask_b32_e32 v12, 0, v12, vcc
	v_cmp_lt_i32_e32 vcc, v16, v128
	v_add_u32_e32 v16, 34, v29
	s_nop 0
	v_cndmask_b32_e32 v13, 0, v13, vcc
	v_cmp_lt_i32_e32 vcc, v16, v128
	v_cvt_pk_bf16_f32 v12, v12, v13
	v_add_u32_e32 v16, 35, v29
	v_cndmask_b32_e32 v14, 0, v14, vcc
	v_cmp_lt_i32_e32 vcc, v16, v128
	s_nop 1
	v_cndmask_b32_e32 v15, 0, v15, vcc
	v_cvt_pk_bf16_f32 v13, v14, v15
	ds_write_b64 v33, v[12:13] offset:64

.LBB0_740:
	v_add_u32_e32 v16, 48, v29
	v_cmp_lt_i32_e32 vcc, v16, v128
	v_add_u32_e32 v16, 49, v29
	s_nop 0
	s_nop 3
	v_cndmask_b32_e32 v12, 0, v12, vcc
	v_cmp_lt_i32_e32 vcc, v16, v128
	v_add_u32_e32 v16, 50, v29
	s_nop 0
	v_cndmask_b32_e32 v13, 0, v13, vcc
	v_cmp_lt_i32_e32 vcc, v16, v128
	v_cvt_pk_bf16_f32 v12, v12, v13
	v_add_u32_e32 v16, 51, v29
	v_cndmask_b32_e32 v14, 0, v14, vcc
	v_cmp_lt_i32_e32 vcc, v16, v128
	s_nop 1
	v_cndmask_b32_e32 v15, 0, v15, vcc
	v_cvt_pk_bf16_f32 v13, v14, v15
	ds_write_b64 v33, v[12:13] offset:96
	s_branch .LBB0_750
